# backward scans: y rows of the forward scan (same block, earlier job) prefetched during the inverse, added in registers, plain stores; no float atomics on Ysum
# speedup vs baseline: 1.0197x; 1.0106x over previous
.LBB0_1149:
	v_mul_u32_u24_e32 v34, 0x48, v70
	v_lshlrev_b32_e32 v66, 1, v34
	s_waitcnt lgkmcnt(0)
	s_barrier
	s_cmp_eq_u64 s[8:9], 0
	s_cbranch_scc1 .Lpf_skip_b
	s_cmp_lg_u64 s[10:11], 0
	s_cbranch_scc1 .Lpf_skip_b
	s_add_i32 s12, s94, 32
	s_add_i32 s12, s12, s87
	s_mov_b32 s13, 0xfffff000
	v_lshlrev_b32_e32 v232, 2, v51
	v_xor_b32_e32 v232, 31, v232
	v_or_b32_e32 v232, s12, v232
	v_lshl_add_u32 v232, v232, 12, v144
	global_load_dword v213, v232, s[56:57] sc1
	v_mad_i32_i24 v230, s13, 1, v232
	global_load_dword v214, v230, s[56:57] sc1
	v_mad_i32_i24 v231, s13, 2, v232
	global_load_dword v215, v231, s[56:57] sc1
	v_mad_i32_i24 v229, s13, 3, v232
	global_load_dword v216, v229, s[56:57] sc1
	v_mad_i32_i24 v230, s13, 8, v232
	global_load_dword v217, v230, s[56:57] sc1
	v_mad_i32_i24 v231, s13, 9, v232
	global_load_dword v218, v231, s[56:57] sc1
	v_mad_i32_i24 v229, s13, 10, v232
	global_load_dword v219, v229, s[56:57] sc1
	v_mad_i32_i24 v230, s13, 11, v232
	global_load_dword v220, v230, s[56:57] sc1
	v_mad_i32_i24 v231, s13, 16, v232
	global_load_dword v221, v231, s[56:57] sc1
	v_mad_i32_i24 v229, s13, 17, v232
	global_load_dword v222, v229, s[56:57] sc1
	v_mad_i32_i24 v230, s13, 18, v232
	global_load_dword v223, v230, s[56:57] sc1
	v_mad_i32_i24 v231, s13, 19, v232
	global_load_dword v224, v231, s[56:57] sc1
	v_mad_i32_i24 v229, s13, 24, v232
	global_load_dword v225, v229, s[56:57] sc1
	v_mad_i32_i24 v230, s13, 25, v232
	global_load_dword v226, v230, s[56:57] sc1
	v_mad_i32_i24 v231, s13, 26, v232
	global_load_dword v227, v231, s[56:57] sc1
	v_mad_i32_i24 v229, s13, 27, v232
	global_load_dword v228, v229, s[56:57] sc1
.Lpf_skip_b:
	v_add3_u32 v50, s89, v66, v0
	ds_read_b128 v[34:37], v50
	v_add3_u32 v0, s90, v66, v0
	ds_read_b128 v[38:41], v0
	ds_read_b128 v[52:55], v50 offset:32
	ds_read_b128 v[56:59], v0 offset:32
	s_mov_b64 s[58:59], -1
	s_and_b64 vcc, exec, s[54:55]
	s_waitcnt lgkmcnt(2)
	v_mfma_f32_32x32x16_bf16 v[34:49], v[34:37], v[38:41], 0
	s_waitcnt lgkmcnt(0)
	v_mfma_f32_32x32x16_bf16 v[34:49], v[52:55], v[56:59], v[34:49]
	ds_read_b128 v[52:55], v50 offset:64
	ds_read_b128 v[56:59], v0 offset:64
	ds_read_b128 v[60:63], v50 offset:96
	ds_read_b128 v[72:75], v0 offset:96
	v_lshlrev_b32_e32 v0, 2, v51
	v_cmp_lt_u32_e64 s[12:13], v70, v0
	v_lshl_add_u32 v50, v70, 1, s91
	s_waitcnt lgkmcnt(2)
	v_mfma_f32_32x32x16_bf16 v[34:49], v[52:55], v[56:59], v[34:49]
	v_cndmask_b32_e64 v52, 0, 1, s[12:13]
	v_cmp_le_u32_e64 s[12:13], v70, v0
	s_nop 1
	v_cndmask_b32_e64 v53, 0, 1, s[12:13]
	v_cndmask_b32_e64 v52, v53, v52, s[8:9]
	v_and_b32_e32 v52, 1, v52
	s_waitcnt lgkmcnt(0)
	v_mfma_f32_32x32x16_bf16 v[34:49], v[60:63], v[72:75], v[34:49]
	v_or_b32_e32 v143, 1, v0
	v_or_b32_e32 v158, 2, v0
	v_or_b32_e32 v159, 3, v0
	v_or_b32_e32 v160, 8, v0
	v_or_b32_e32 v161, 9, v0
	v_or_b32_e32 v162, 10, v0
	v_or_b32_e32 v163, 11, v0
	v_or_b32_e32 v164, 16, v0
	v_or_b32_e32 v165, 17, v0
	v_or_b32_e32 v166, 18, v0
	v_or_b32_e32 v167, 19, v0
	v_or_b32_e32 v168, 24, v0
	v_or_b32_e32 v169, 25, v0
	v_or_b32_e32 v170, 26, v0
	v_or_b32_e32 v171, 27, v0
	s_cmp_eq_u64 s[54:55], 0
	s_cbranch_scc1 .Ld_w0_b
	s_cmp_lg_u32 s89, s69
	s_cbranch_scc1 .Ld_w23_b
	v_mul_u32_u24_e32 v52, 0x50, v0
	v_add_u32_e32 v52, v52, v50
	v_cmp_lt_u32_e32 vcc, v70, v0
	v_cmp_lt_u32_e64 s[12:13], v70, v143
	v_cmp_lt_u32_e64 s[58:59], v70, v158
	v_cndmask_b32_e64 v34, 0, v34, vcc
	v_cmp_lt_u32_e32 vcc, v70, v159
	v_cndmask_b32_e64 v35, 0, v35, s[12:13]
	v_cmp_lt_u32_e64 s[12:13], v70, v160
	v_cvt_pk_bf16_f32 v53, v34, v35
	ds_write_b16 v52, v53 offset:0
	ds_write_b16_d16_hi v52, v53 offset:80
	v_cndmask_b32_e64 v36, 0, v36, s[58:59]
	v_cmp_lt_u32_e64 s[58:59], v70, v161
	v_cndmask_b32_e64 v37, 0, v37, vcc
	v_cmp_lt_u32_e32 vcc, v70, v162
	v_cvt_pk_bf16_f32 v53, v36, v37
	ds_write_b16 v52, v53 offset:160
	ds_write_b16_d16_hi v52, v53 offset:240
	v_cndmask_b32_e64 v38, 0, v38, s[12:13]
	v_cmp_lt_u32_e64 s[12:13], v70, v163
	v_cndmask_b32_e64 v39, 0, v39, s[58:59]
	v_cmp_lt_u32_e64 s[58:59], v70, v164
	v_cvt_pk_bf16_f32 v53, v38, v39
	ds_write_b16 v52, v53 offset:640
	ds_write_b16_d16_hi v52, v53 offset:720
	v_cndmask_b32_e64 v40, 0, v40, vcc
	v_cmp_lt_u32_e32 vcc, v70, v165
	v_cndmask_b32_e64 v41, 0, v41, s[12:13]
	v_cmp_lt_u32_e64 s[12:13], v70, v166
	v_cvt_pk_bf16_f32 v53, v40, v41
	ds_write_b16 v52, v53 offset:800
	ds_write_b16_d16_hi v52, v53 offset:880
	v_cndmask_b32_e64 v42, 0, v42, s[58:59]
	v_cmp_lt_u32_e64 s[58:59], v70, v167
	v_cndmask_b32_e64 v43, 0, v43, vcc
	v_cmp_lt_u32_e32 vcc, v70, v168
	v_cvt_pk_bf16_f32 v53, v42, v43
	ds_write_b16 v52, v53 offset:1280
	ds_write_b16_d16_hi v52, v53 offset:1360
	v_cndmask_b32_e64 v44, 0, v44, s[12:13]
	v_cmp_lt_u32_e64 s[12:13], v70, v169
	v_cndmask_b32_e64 v45, 0, v45, s[58:59]
	v_cmp_lt_u32_e64 s[58:59], v70, v170
	v_cvt_pk_bf16_f32 v53, v44, v45
	ds_write_b16 v52, v53 offset:1440
	ds_write_b16_d16_hi v52, v53 offset:1520
	v_cndmask_b32_e64 v46, 0, v46, vcc
	v_cmp_lt_u32_e32 vcc, v70, v171
	v_cndmask_b32_e64 v47, 0, v47, s[12:13]
	v_cvt_pk_bf16_f32 v53, v46, v47
	ds_write_b16 v52, v53 offset:1920
	ds_write_b16_d16_hi v52, v53 offset:2000
	v_cndmask_b32_e64 v48, 0, v48, s[58:59]
	v_cndmask_b32_e64 v49, 0, v49, vcc
	v_cvt_pk_bf16_f32 v53, v48, v49
	ds_write_b16 v52, v53 offset:2080
	ds_write_b16_d16_hi v52, v53 offset:2160
	s_branch .Ld_done_b

.Le23_skip_b:
	s_waitcnt lgkmcnt(0)
	s_barrier
	s_andn2_b64 vcc, exec, s[8:9]
	s_cbranch_vccnz .LBB0_1106
	v_lshlrev_b32_e32 v80, 1, v0
	v_add_u32_e32 v46, v66, v80
	v_add_u32_e32 v47, 0x4000, v46
	ds_read2_b64 v[34:37], v47 offset0:32 offset1:34
	v_cvt_pk_bf16_f32 v38, v18, v19
	v_cvt_pk_bf16_f32 v39, v20, v21
	v_cvt_pk_bf16_f32 v40, v22, v23
	v_cvt_pk_bf16_f32 v41, v24, v25
	ds_read2_b64 v[42:45], v47 offset0:36 offset1:38
	v_lshlrev_b32_e32 v48, 3, v51
	v_cvt_pk_bf16_f32 v72, v26, v27
	v_cvt_pk_bf16_f32 v73, v28, v29
	s_waitcnt lgkmcnt(1)
	v_mfma_f32_32x32x16_bf16 v[50:65], v[34:37], v[38:41], 0
	v_cvt_pk_bf16_f32 v74, v30, v31
	v_cvt_pk_bf16_f32 v75, v32, v33
	ds_read2_b64 v[34:37], v47 offset0:40 offset1:42
	v_cvt_pk_bf16_f32 v76, v2, v3
	v_cvt_pk_bf16_f32 v77, v4, v5
	v_cvt_pk_bf16_f32 v78, v6, v7
	v_cvt_pk_bf16_f32 v79, v8, v9
	s_waitcnt lgkmcnt(1)
	v_mfma_f32_32x32x16_bf16 v[50:65], v[42:45], v[72:75], v[50:65]
	ds_read2_b64 v[42:45], v47 offset0:44 offset1:46
	v_cvt_pk_bf16_f32 v172, v10, v11
	v_cvt_pk_bf16_f32 v173, v12, v13
	v_cvt_pk_bf16_f32 v174, v14, v15
	v_cvt_pk_bf16_f32 v175, v16, v17
	v_mov_b32_e32 v49, s92
	v_bitop3_b32 v47, v48, v141, 24 bitop3:0x78
	s_waitcnt lgkmcnt(1)
	v_mfma_f32_32x32x16_bf16 v[50:65], v[34:37], v[76:79], v[50:65]
	v_lshlrev_b32_e32 v34, 6, v70
	v_sub_u32_e32 v177, v66, v34
	v_lshl_add_u32 v70, v48, 1, v177
	ds_read_b128 v[34:37], v70 offset:50624
	v_mad_u32_u24 v49, v71, s77, v49
	v_lshlrev_b32_e32 v207, 1, v47
	v_and_b32_e32 v145, 24, v141
	s_waitcnt lgkmcnt(1)
	v_mfma_f32_32x32x16_bf16 v[50:65], v[42:45], v[172:175], v[50:65]
	v_add_u32_e32 v42, v49, v207
	ds_read_b128 v[130:133], v42 offset:45440
	v_bitop3_b32 v67, v48, v145, 16 bitop3:0x36
	v_lshlrev_b32_e32 v212, 1, v67
	v_add_u32_e32 v71, 0x5000, v46
	v_add_u32_e32 v47, v49, v212
	ds_read_b128 v[42:45], v70 offset:50656
	ds_read_b128 v[126:129], v47 offset:45440
	s_waitcnt lgkmcnt(2)
	v_mfma_f32_32x32x16_bf16 v[50:65], v[34:37], v[130:133], v[50:65]
	ds_read2_b64 v[34:37], v71 offset0:96 offset1:98
	ds_read2_b64 v[66:69], v71 offset0:100 offset1:102
	ds_read2_b64 v[178:181], v71 offset0:104 offset1:106
	ds_read2_b64 v[182:185], v71 offset0:108 offset1:110
	ds_read_b128 v[186:189], v70 offset:55744
	ds_read_b128 v[190:193], v70 offset:55776
	v_lshlrev_b32_e32 v81, 2, v0
	s_sub_i32 s58, s93, 32
	s_add_i32 s59, s94, 32
	s_and_b64 s[12:13], s[10:11], exec
	s_waitcnt lgkmcnt(6)
	v_mfma_f32_32x32x16_bf16 v[50:65], v[42:45], v[126:129], v[50:65]
	s_cselect_b32 s12, s58, s59
	s_add_i32 s12, s12, s87
	s_waitcnt lgkmcnt(5)
	v_mfma_f32_32x32x16_bf16 v[34:49], v[34:37], v[38:41], 0
	s_nop 7
	v_cvt_pk_bf16_f32 v50, v50, v51
	v_cvt_pk_bf16_f32 v51, v52, v53
	v_cvt_pk_bf16_f32 v52, v54, v55
	v_cvt_pk_bf16_f32 v53, v56, v57
	s_waitcnt lgkmcnt(4)
	v_mfma_f32_32x32x16_bf16 v[34:49], v[66:69], v[72:75], v[34:49]
	ds_read_b128 v[66:69], v81 offset:60928
	ds_read_b128 v[70:73], v81 offset:60960
	ds_read_b128 v[194:197], v81 offset:60864
	ds_read_b128 v[198:201], v81 offset:60896
	ds_read_b128 v[202:205], v81 offset:60992
	ds_read_b128 v[208:211], v81 offset:61024
	s_waitcnt lgkmcnt(4)
	v_pk_mul_f32 v[30:31], v[30:31], v[70:71]
	v_pk_mul_f32 v[26:27], v[26:27], v[66:67]
	v_pk_mul_f32 v[32:33], v[32:33], v[72:73]
	v_pk_mul_f32 v[28:29], v[28:29], v[68:69]
	ds_read_b128 v[66:69], v81 offset:61056
	ds_read_b128 v[70:73], v81 offset:61088
	s_waitcnt lgkmcnt(4)
	v_pk_mul_f32 v[22:23], v[22:23], v[198:199]
	v_mfma_f32_32x32x16_bf16 v[34:49], v[178:181], v[76:79], v[34:49]
	v_mul_f32_e64 v24, v24, v200
	v_mul_f32_e64 v25, v25, v201
	s_waitcnt lgkmcnt(1)
	v_mul_f32_e64 v10, v10, v66
	v_mul_f32_e64 v11, v11, v67
	s_waitcnt lgkmcnt(0)
	v_pk_mul_f32 v[14:15], v[14:15], v[70:71]
	v_pk_mul_f32 v[16:17], v[16:17], v[72:73]
	v_pk_mul_f32 v[12:13], v[12:13], v[68:69]
	v_pk_mul_f32 v[20:21], v[20:21], v[196:197]
	v_pk_mul_f32 v[18:19], v[18:19], v[194:195]
	v_mfma_f32_32x32x16_bf16 v[34:49], v[182:185], v[172:175], v[34:49]
	v_add_u32_e32 v172, v177, v80
	v_add_u32_e32 v66, 0xe000, v172
	ds_read2_b64 v[74:77], v66 offset0:120 offset1:122
	ds_read2_b64 v[54:57], v66 offset0:124 offset1:126
	v_mul_f32_e64 v6, v6, v208
	v_mul_f32_e64 v7, v7, v209
	v_pk_mul_f32 v[8:9], v[8:9], v[210:211]
	v_pk_mul_f32 v[4:5], v[4:5], v[204:205]
	s_waitcnt lgkmcnt(1)
	v_mfma_f32_32x32x16_bf16 v[66:81], v[74:77], v[50:53], 0
	v_cvt_pk_bf16_f32 v50, v58, v59
	v_cvt_pk_bf16_f32 v51, v60, v61
	v_cvt_pk_bf16_f32 v52, v62, v63
	v_cvt_pk_bf16_f32 v53, v64, v65
	v_add_u32_e32 v62, v177, v212
	v_pk_mul_f32 v[2:3], v[2:3], v[202:203]
	s_waitcnt lgkmcnt(0)
	v_mfma_f32_32x32x16_bf16 v[66:81], v[54:57], v[50:53], v[66:81]
	v_add_u32_e32 v54, v177, v207
	ds_read_b128 v[50:53], v54 offset:40256
	ds_read_b128 v[54:57], v54 offset:42880
	ds_read_b128 v[58:61], v62 offset:40256
	ds_read_b128 v[62:65], v62 offset:42880
	s_nop 6
	v_cvt_pk_bf16_f32 v66, v66, v67
	v_mfma_f32_32x32x16_bf16 v[34:49], v[186:189], v[130:133], v[34:49]
	v_cvt_pk_bf16_f32 v67, v68, v69
	v_cvt_pk_bf16_f32 v68, v70, v71
	v_cvt_pk_bf16_f32 v69, v72, v73
	v_cvt_pk_bf16_f32 v70, v74, v75
	v_cvt_pk_bf16_f32 v72, v78, v79
	v_add_u32_e32 v78, 0xc800, v172
	v_lshl_add_u32 v74, v145, 1, v172
	s_waitcnt lgkmcnt(3)
	v_mfma_f32_32x32x16_bf16 v[18:33], v[50:53], v[130:133], v[18:33]
	v_bitop3_b32 v50, v141, 8, 24 bitop3:0x6c
	v_lshl_add_u32 v75, v50, 1, v172
	v_bitop3_b32 v50, v141, 16, 24 bitop3:0x6c
	v_lshl_add_u32 v145, v50, 1, v172
	ds_read2_b64 v[50:53], v78 offset0:248 offset1:250
	v_cvt_pk_bf16_f32 v71, v76, v77
	v_cvt_pk_bf16_f32 v73, v80, v81
	v_mfma_f32_32x32x16_bf16 v[34:49], v[190:193], v[126:129], v[34:49]
	s_waitcnt lgkmcnt(0)
	v_mfma_f32_32x32x16_bf16 v[34:49], v[50:53], v[66:69], v[34:49]
	v_mfma_f32_32x32x16_bf16 v[18:33], v[58:61], v[126:129], v[18:33]
	v_bitop3_b32 v58, v141, 24, v141 bitop3:0xc
	v_lshl_add_u32 v141, v58, 1, v172
	ds_read_b64 v[58:59], v74 offset:35072
	ds_read_b64 v[60:61], v75 offset:35072
	ds_read_b64 v[76:77], v75 offset:37696
	ds_read_b64 v[74:75], v74 offset:37696
	ds_read2_b64 v[78:81], v78 offset0:252 offset1:254
	ds_read_b64 v[50:51], v145 offset:35072
	ds_read_b64 v[52:53], v141 offset:35072
	ds_read_b64 v[174:175], v141 offset:37696
	ds_read_b64 v[172:173], v145 offset:37696
	v_xor_b32_e32 v141, 31, v0
	v_cndmask_b32_e64 v141, v141, v0, s[10:11]
	v_mov_b32_e32 v145, v1
	s_waitcnt lgkmcnt(4)
	v_mfma_f32_32x32x16_bf16 v[34:49], v[78:81], v[70:73], v[34:49]
	v_or_b32_e32 v78, s12, v141
	v_lshl_add_u32 v78, v78, 12, v144
	s_movk_i32 s13, 0x1000
	s_and_b64 vcc, exec, s[10:11]
	s_cselect_b32 s13, s13, 0xfffff000
	v_mfma_f32_32x32x16_bf16 v[2:17], v[54:57], v[130:133], v[2:17]
	s_cbranch_vccnz .Lys_fwd
	s_nop 6
	s_waitcnt vmcnt(0)
	v_add_f32_e32 v34, v34, v213
	global_store_dword v78, v34, s[56:57]
	v_mad_i32_i24 v80, s13, 1, v78
	v_add_f32_e32 v35, v35, v214
	global_store_dword v80, v35, s[56:57]
	v_mad_i32_i24 v81, s13, 2, v78
	v_add_f32_e32 v36, v36, v215
	global_store_dword v81, v36, s[56:57]
	v_mad_i32_i24 v79, s13, 3, v78
	v_add_f32_e32 v37, v37, v216
	global_store_dword v79, v37, s[56:57]
	v_mad_i32_i24 v80, s13, 8, v78
	v_add_f32_e32 v38, v38, v217
	global_store_dword v80, v38, s[56:57]
	v_mad_i32_i24 v81, s13, 9, v78
	v_add_f32_e32 v39, v39, v218
	global_store_dword v81, v39, s[56:57]
	v_mad_i32_i24 v79, s13, 10, v78
	v_add_f32_e32 v40, v40, v219
	global_store_dword v79, v40, s[56:57]
	v_mad_i32_i24 v80, s13, 11, v78
	v_add_f32_e32 v41, v41, v220
	global_store_dword v80, v41, s[56:57]
	v_mad_i32_i24 v81, s13, 16, v78
	v_add_f32_e32 v42, v42, v221
	global_store_dword v81, v42, s[56:57]
	v_mad_i32_i24 v79, s13, 17, v78
	v_add_f32_e32 v43, v43, v222
	global_store_dword v79, v43, s[56:57]
	v_mad_i32_i24 v80, s13, 18, v78
	v_add_f32_e32 v44, v44, v223
	global_store_dword v80, v44, s[56:57]
	v_mad_i32_i24 v81, s13, 19, v78
	v_add_f32_e32 v45, v45, v224
	global_store_dword v81, v45, s[56:57]
	v_mad_i32_i24 v79, s13, 24, v78
	v_add_f32_e32 v46, v46, v225
	global_store_dword v79, v46, s[56:57]
	v_mad_i32_i24 v80, s13, 25, v78
	v_add_f32_e32 v47, v47, v226
	global_store_dword v80, v47, s[56:57]
	v_mad_i32_i24 v81, s13, 26, v78
	v_add_f32_e32 v48, v48, v227
	global_store_dword v81, v48, s[56:57]
	v_mad_i32_i24 v79, s13, 27, v78
	v_add_f32_e32 v49, v49, v228
	global_store_dword v79, v49, s[56:57]
	s_branch .Lys_join

.LBB0_1278:
	v_mul_u32_u24_e32 v34, 0x48, v70
	v_lshlrev_b32_e32 v66, 1, v34
	s_waitcnt lgkmcnt(0)
	s_barrier
	s_cmp_eq_u64 s[8:9], 0
	s_cbranch_scc1 .Lpf_skip_c
	s_cmp_lg_u64 s[10:11], 0
	s_cbranch_scc1 .Lpf_skip_c
	s_add_i32 s12, s89, 32
	s_add_i32 s12, s12, s83
	s_mov_b32 s13, 0xfffff000
	v_lshlrev_b32_e32 v232, 2, v51
	v_xor_b32_e32 v232, 31, v232
	v_or_b32_e32 v232, s12, v232
	v_lshl_add_u32 v232, v232, 12, v144
	global_load_dword v213, v232, s[56:57] sc1
	v_mad_i32_i24 v230, s13, 1, v232
	global_load_dword v214, v230, s[56:57] sc1
	v_mad_i32_i24 v231, s13, 2, v232
	global_load_dword v215, v231, s[56:57] sc1
	v_mad_i32_i24 v229, s13, 3, v232
	global_load_dword v216, v229, s[56:57] sc1
	v_mad_i32_i24 v230, s13, 8, v232
	global_load_dword v217, v230, s[56:57] sc1
	v_mad_i32_i24 v231, s13, 9, v232
	global_load_dword v218, v231, s[56:57] sc1
	v_mad_i32_i24 v229, s13, 10, v232
	global_load_dword v219, v229, s[56:57] sc1
	v_mad_i32_i24 v230, s13, 11, v232
	global_load_dword v220, v230, s[56:57] sc1
	v_mad_i32_i24 v231, s13, 16, v232
	global_load_dword v221, v231, s[56:57] sc1
	v_mad_i32_i24 v229, s13, 17, v232
	global_load_dword v222, v229, s[56:57] sc1
	v_mad_i32_i24 v230, s13, 18, v232
	global_load_dword v223, v230, s[56:57] sc1
	v_mad_i32_i24 v231, s13, 19, v232
	global_load_dword v224, v231, s[56:57] sc1
	v_mad_i32_i24 v229, s13, 24, v232
	global_load_dword v225, v229, s[56:57] sc1
	v_mad_i32_i24 v230, s13, 25, v232
	global_load_dword v226, v230, s[56:57] sc1
	v_mad_i32_i24 v231, s13, 26, v232
	global_load_dword v227, v231, s[56:57] sc1
	v_mad_i32_i24 v229, s13, 27, v232
	global_load_dword v228, v229, s[56:57] sc1
.Lpf_skip_c:
	v_add3_u32 v50, s85, v66, v0
	ds_read_b128 v[34:37], v50
	v_add3_u32 v0, s86, v66, v0
	ds_read_b128 v[38:41], v0
	ds_read_b128 v[52:55], v50 offset:32
	ds_read_b128 v[56:59], v0 offset:32
	s_mov_b64 s[58:59], -1
	s_and_b64 vcc, exec, s[54:55]
	s_waitcnt lgkmcnt(2)
	v_mfma_f32_32x32x16_bf16 v[34:49], v[34:37], v[38:41], 0
	s_waitcnt lgkmcnt(0)
	v_mfma_f32_32x32x16_bf16 v[34:49], v[52:55], v[56:59], v[34:49]
	ds_read_b128 v[52:55], v50 offset:64
	ds_read_b128 v[56:59], v0 offset:64
	ds_read_b128 v[60:63], v50 offset:96
	ds_read_b128 v[72:75], v0 offset:96
	v_lshlrev_b32_e32 v0, 2, v51
	v_cmp_lt_u32_e64 s[12:13], v70, v0
	v_lshl_add_u32 v50, v70, 1, s87
	s_waitcnt lgkmcnt(2)
	v_mfma_f32_32x32x16_bf16 v[34:49], v[52:55], v[56:59], v[34:49]
	v_cndmask_b32_e64 v52, 0, 1, s[12:13]
	v_cmp_le_u32_e64 s[12:13], v70, v0
	s_nop 1
	v_cndmask_b32_e64 v53, 0, 1, s[12:13]
	v_cndmask_b32_e64 v52, v53, v52, s[8:9]
	v_and_b32_e32 v52, 1, v52
	s_waitcnt lgkmcnt(0)
	v_mfma_f32_32x32x16_bf16 v[34:49], v[60:63], v[72:75], v[34:49]
	v_or_b32_e32 v143, 1, v0
	v_or_b32_e32 v158, 2, v0
	v_or_b32_e32 v159, 3, v0
	v_or_b32_e32 v160, 8, v0
	v_or_b32_e32 v161, 9, v0
	v_or_b32_e32 v162, 10, v0
	v_or_b32_e32 v163, 11, v0
	v_or_b32_e32 v164, 16, v0
	v_or_b32_e32 v165, 17, v0
	v_or_b32_e32 v166, 18, v0
	v_or_b32_e32 v167, 19, v0
	v_or_b32_e32 v168, 24, v0
	v_or_b32_e32 v169, 25, v0
	v_or_b32_e32 v170, 26, v0
	v_or_b32_e32 v171, 27, v0
	s_cmp_eq_u64 s[54:55], 0
	s_cbranch_scc1 .Ld_w0_c
	s_cmp_lg_u32 s85, s69
	s_cbranch_scc1 .Ld_w23_c
	v_mul_u32_u24_e32 v52, 0x50, v0
	v_add_u32_e32 v52, v52, v50
	v_cmp_lt_u32_e32 vcc, v70, v0
	v_cmp_lt_u32_e64 s[12:13], v70, v143
	v_cmp_lt_u32_e64 s[58:59], v70, v158
	v_cndmask_b32_e64 v34, 0, v34, vcc
	v_cmp_lt_u32_e32 vcc, v70, v159
	v_cndmask_b32_e64 v35, 0, v35, s[12:13]
	v_cmp_lt_u32_e64 s[12:13], v70, v160
	v_cvt_pk_bf16_f32 v53, v34, v35
	ds_write_b16 v52, v53 offset:0
	ds_write_b16_d16_hi v52, v53 offset:80
	v_cndmask_b32_e64 v36, 0, v36, s[58:59]
	v_cmp_lt_u32_e64 s[58:59], v70, v161
	v_cndmask_b32_e64 v37, 0, v37, vcc
	v_cmp_lt_u32_e32 vcc, v70, v162
	v_cvt_pk_bf16_f32 v53, v36, v37
	ds_write_b16 v52, v53 offset:160
	ds_write_b16_d16_hi v52, v53 offset:240
	v_cndmask_b32_e64 v38, 0, v38, s[12:13]
	v_cmp_lt_u32_e64 s[12:13], v70, v163
	v_cndmask_b32_e64 v39, 0, v39, s[58:59]
	v_cmp_lt_u32_e64 s[58:59], v70, v164
	v_cvt_pk_bf16_f32 v53, v38, v39
	ds_write_b16 v52, v53 offset:640
	ds_write_b16_d16_hi v52, v53 offset:720
	v_cndmask_b32_e64 v40, 0, v40, vcc
	v_cmp_lt_u32_e32 vcc, v70, v165
	v_cndmask_b32_e64 v41, 0, v41, s[12:13]
	v_cmp_lt_u32_e64 s[12:13], v70, v166
	v_cvt_pk_bf16_f32 v53, v40, v41
	ds_write_b16 v52, v53 offset:800
	ds_write_b16_d16_hi v52, v53 offset:880
	v_cndmask_b32_e64 v42, 0, v42, s[58:59]
	v_cmp_lt_u32_e64 s[58:59], v70, v167
	v_cndmask_b32_e64 v43, 0, v43, vcc
	v_cmp_lt_u32_e32 vcc, v70, v168
	v_cvt_pk_bf16_f32 v53, v42, v43
	ds_write_b16 v52, v53 offset:1280
	ds_write_b16_d16_hi v52, v53 offset:1360
	v_cndmask_b32_e64 v44, 0, v44, s[12:13]
	v_cmp_lt_u32_e64 s[12:13], v70, v169
	v_cndmask_b32_e64 v45, 0, v45, s[58:59]
	v_cmp_lt_u32_e64 s[58:59], v70, v170
	v_cvt_pk_bf16_f32 v53, v44, v45
	ds_write_b16 v52, v53 offset:1440
	ds_write_b16_d16_hi v52, v53 offset:1520
	v_cndmask_b32_e64 v46, 0, v46, vcc
	v_cmp_lt_u32_e32 vcc, v70, v171
	v_cndmask_b32_e64 v47, 0, v47, s[12:13]
	v_cvt_pk_bf16_f32 v53, v46, v47
	ds_write_b16 v52, v53 offset:1920
	ds_write_b16_d16_hi v52, v53 offset:2000
	v_cndmask_b32_e64 v48, 0, v48, s[58:59]
	v_cndmask_b32_e64 v49, 0, v49, vcc
	v_cvt_pk_bf16_f32 v53, v48, v49
	ds_write_b16 v52, v53 offset:2080
	ds_write_b16_d16_hi v52, v53 offset:2160
	s_branch .Ld_done_c

.Le23_skip_c:
	s_waitcnt lgkmcnt(0)
	s_barrier
	s_andn2_b64 vcc, exec, s[8:9]
	s_cbranch_vccnz .LBB0_1235
	v_lshlrev_b32_e32 v80, 1, v0
	v_add_u32_e32 v46, v66, v80
	v_add_u32_e32 v47, 0x4000, v46
	ds_read2_b64 v[34:37], v47 offset0:32 offset1:34
	v_cvt_pk_bf16_f32 v38, v18, v19
	v_cvt_pk_bf16_f32 v39, v20, v21
	v_cvt_pk_bf16_f32 v40, v22, v23
	v_cvt_pk_bf16_f32 v41, v24, v25
	ds_read2_b64 v[42:45], v47 offset0:36 offset1:38
	v_lshlrev_b32_e32 v48, 3, v51
	v_cvt_pk_bf16_f32 v72, v26, v27
	v_cvt_pk_bf16_f32 v73, v28, v29
	s_waitcnt lgkmcnt(1)
	v_mfma_f32_32x32x16_bf16 v[50:65], v[34:37], v[38:41], 0
	v_cvt_pk_bf16_f32 v74, v30, v31
	v_cvt_pk_bf16_f32 v75, v32, v33
	ds_read2_b64 v[34:37], v47 offset0:40 offset1:42
	v_cvt_pk_bf16_f32 v76, v2, v3
	v_cvt_pk_bf16_f32 v77, v4, v5
	v_cvt_pk_bf16_f32 v78, v6, v7
	v_cvt_pk_bf16_f32 v79, v8, v9
	s_waitcnt lgkmcnt(1)
	v_mfma_f32_32x32x16_bf16 v[50:65], v[42:45], v[72:75], v[50:65]
	ds_read2_b64 v[42:45], v47 offset0:44 offset1:46
	v_cvt_pk_bf16_f32 v172, v10, v11
	v_cvt_pk_bf16_f32 v173, v12, v13
	v_cvt_pk_bf16_f32 v174, v14, v15
	v_cvt_pk_bf16_f32 v175, v16, v17
	v_mov_b32_e32 v49, s88
	v_bitop3_b32 v47, v48, v141, 24 bitop3:0x78
	s_waitcnt lgkmcnt(1)
	v_mfma_f32_32x32x16_bf16 v[50:65], v[34:37], v[76:79], v[50:65]
	v_lshlrev_b32_e32 v34, 6, v70
	v_sub_u32_e32 v177, v66, v34
	v_lshl_add_u32 v70, v48, 1, v177
	ds_read_b128 v[34:37], v70 offset:50624
	v_mad_u32_u24 v49, v71, s77, v49
	v_lshlrev_b32_e32 v207, 1, v47
	v_and_b32_e32 v145, 24, v141
	s_waitcnt lgkmcnt(1)
	v_mfma_f32_32x32x16_bf16 v[50:65], v[42:45], v[172:175], v[50:65]
	v_add_u32_e32 v42, v49, v207
	ds_read_b128 v[130:133], v42 offset:45440
	v_bitop3_b32 v67, v48, v145, 16 bitop3:0x36
	v_lshlrev_b32_e32 v212, 1, v67
	v_add_u32_e32 v71, 0x5000, v46
	v_add_u32_e32 v47, v49, v212
	ds_read_b128 v[42:45], v70 offset:50656
	ds_read_b128 v[126:129], v47 offset:45440
	s_waitcnt lgkmcnt(2)
	v_mfma_f32_32x32x16_bf16 v[50:65], v[34:37], v[130:133], v[50:65]
	ds_read2_b64 v[34:37], v71 offset0:96 offset1:98
	ds_read2_b64 v[66:69], v71 offset0:100 offset1:102
	ds_read2_b64 v[178:181], v71 offset0:104 offset1:106
	ds_read2_b64 v[182:185], v71 offset0:108 offset1:110
	ds_read_b128 v[186:189], v70 offset:55744
	ds_read_b128 v[190:193], v70 offset:55776
	v_lshlrev_b32_e32 v81, 2, v0
	s_add_i32 s58, s89, 32
	s_and_b64 s[12:13], s[10:11], exec
	s_cselect_b32 s12, s91, s58
	s_waitcnt lgkmcnt(6)
	v_mfma_f32_32x32x16_bf16 v[50:65], v[42:45], v[126:129], v[50:65]
	s_add_i32 s12, s12, s83
	s_waitcnt lgkmcnt(5)
	v_mfma_f32_32x32x16_bf16 v[34:49], v[34:37], v[38:41], 0
	s_nop 8
	v_cvt_pk_bf16_f32 v50, v50, v51
	v_cvt_pk_bf16_f32 v51, v52, v53
	v_cvt_pk_bf16_f32 v52, v54, v55
	v_cvt_pk_bf16_f32 v53, v56, v57
	s_waitcnt lgkmcnt(4)
	v_mfma_f32_32x32x16_bf16 v[34:49], v[66:69], v[72:75], v[34:49]
	ds_read_b128 v[66:69], v81 offset:60928
	ds_read_b128 v[70:73], v81 offset:60960
	ds_read_b128 v[194:197], v81 offset:60864
	ds_read_b128 v[198:201], v81 offset:60896
	ds_read_b128 v[202:205], v81 offset:60992
	ds_read_b128 v[208:211], v81 offset:61024
	s_waitcnt lgkmcnt(4)
	v_pk_mul_f32 v[30:31], v[30:31], v[70:71]
	v_pk_mul_f32 v[26:27], v[26:27], v[66:67]
	v_pk_mul_f32 v[32:33], v[32:33], v[72:73]
	v_pk_mul_f32 v[28:29], v[28:29], v[68:69]
	ds_read_b128 v[66:69], v81 offset:61056
	ds_read_b128 v[70:73], v81 offset:61088
	s_waitcnt lgkmcnt(4)
	v_pk_mul_f32 v[22:23], v[22:23], v[198:199]
	v_mfma_f32_32x32x16_bf16 v[34:49], v[178:181], v[76:79], v[34:49]
	v_mul_f32_e64 v24, v24, v200
	v_mul_f32_e64 v25, v25, v201
	s_waitcnt lgkmcnt(1)
	v_mul_f32_e64 v10, v10, v66
	v_mul_f32_e64 v11, v11, v67
	s_waitcnt lgkmcnt(0)
	v_pk_mul_f32 v[14:15], v[14:15], v[70:71]
	v_pk_mul_f32 v[16:17], v[16:17], v[72:73]
	v_pk_mul_f32 v[12:13], v[12:13], v[68:69]
	v_pk_mul_f32 v[20:21], v[20:21], v[196:197]
	v_pk_mul_f32 v[18:19], v[18:19], v[194:195]
	v_mfma_f32_32x32x16_bf16 v[34:49], v[182:185], v[172:175], v[34:49]
	v_add_u32_e32 v172, v177, v80
	v_add_u32_e32 v66, 0xe000, v172
	ds_read2_b64 v[74:77], v66 offset0:120 offset1:122
	ds_read2_b64 v[54:57], v66 offset0:124 offset1:126
	v_mul_f32_e64 v6, v6, v208
	v_mul_f32_e64 v7, v7, v209
	v_pk_mul_f32 v[8:9], v[8:9], v[210:211]
	v_pk_mul_f32 v[4:5], v[4:5], v[204:205]
	s_waitcnt lgkmcnt(1)
	v_mfma_f32_32x32x16_bf16 v[66:81], v[74:77], v[50:53], 0
	v_cvt_pk_bf16_f32 v50, v58, v59
	v_cvt_pk_bf16_f32 v51, v60, v61
	v_cvt_pk_bf16_f32 v52, v62, v63
	v_cvt_pk_bf16_f32 v53, v64, v65
	v_add_u32_e32 v62, v177, v212
	v_pk_mul_f32 v[2:3], v[2:3], v[202:203]
	s_waitcnt lgkmcnt(0)
	v_mfma_f32_32x32x16_bf16 v[66:81], v[54:57], v[50:53], v[66:81]
	v_add_u32_e32 v54, v177, v207
	ds_read_b128 v[50:53], v54 offset:40256
	ds_read_b128 v[54:57], v54 offset:42880
	ds_read_b128 v[58:61], v62 offset:40256
	ds_read_b128 v[62:65], v62 offset:42880
	s_nop 6
	v_cvt_pk_bf16_f32 v66, v66, v67
	v_mfma_f32_32x32x16_bf16 v[34:49], v[186:189], v[130:133], v[34:49]
	v_cvt_pk_bf16_f32 v67, v68, v69
	v_cvt_pk_bf16_f32 v68, v70, v71
	v_cvt_pk_bf16_f32 v69, v72, v73
	v_cvt_pk_bf16_f32 v70, v74, v75
	v_cvt_pk_bf16_f32 v72, v78, v79
	v_add_u32_e32 v78, 0xc800, v172
	v_lshl_add_u32 v74, v145, 1, v172
	s_waitcnt lgkmcnt(3)
	v_mfma_f32_32x32x16_bf16 v[18:33], v[50:53], v[130:133], v[18:33]
	v_bitop3_b32 v50, v141, 8, 24 bitop3:0x6c
	v_lshl_add_u32 v75, v50, 1, v172
	v_bitop3_b32 v50, v141, 16, 24 bitop3:0x6c
	v_lshl_add_u32 v145, v50, 1, v172
	ds_read2_b64 v[50:53], v78 offset0:248 offset1:250
	v_cvt_pk_bf16_f32 v71, v76, v77
	v_cvt_pk_bf16_f32 v73, v80, v81
	v_mfma_f32_32x32x16_bf16 v[34:49], v[190:193], v[126:129], v[34:49]
	s_waitcnt lgkmcnt(0)
	v_mfma_f32_32x32x16_bf16 v[34:49], v[50:53], v[66:69], v[34:49]
	v_mfma_f32_32x32x16_bf16 v[18:33], v[58:61], v[126:129], v[18:33]
	v_bitop3_b32 v58, v141, 24, v141 bitop3:0xc
	v_lshl_add_u32 v141, v58, 1, v172
	ds_read_b64 v[58:59], v74 offset:35072
	ds_read_b64 v[60:61], v75 offset:35072
	ds_read_b64 v[76:77], v75 offset:37696
	ds_read_b64 v[74:75], v74 offset:37696
	ds_read2_b64 v[78:81], v78 offset0:252 offset1:254
	ds_read_b64 v[50:51], v145 offset:35072
	ds_read_b64 v[52:53], v141 offset:35072
	ds_read_b64 v[174:175], v141 offset:37696
	ds_read_b64 v[172:173], v145 offset:37696
	v_xor_b32_e32 v141, 31, v0
	v_cndmask_b32_e64 v141, v141, v0, s[10:11]
	s_waitcnt lgkmcnt(4)
	v_mfma_f32_32x32x16_bf16 v[34:49], v[78:81], v[70:73], v[34:49]
	v_or_b32_e32 v78, s12, v141
	v_lshl_add_u32 v78, v78, 12, v144
	s_movk_i32 s13, 0x1000
	s_and_b64 vcc, exec, s[10:11]
	s_cselect_b32 s13, s13, 0xfffff000
	v_mfma_f32_32x32x16_bf16 v[2:17], v[54:57], v[130:133], v[2:17]
	s_cbranch_vccnz .Lys3_fwd
	s_nop 6
	s_waitcnt vmcnt(0)
	v_add_f32_e32 v34, v34, v213
	global_store_dword v78, v34, s[56:57]
	v_mad_i32_i24 v80, s13, 1, v78
	v_add_f32_e32 v35, v35, v214
	global_store_dword v80, v35, s[56:57]
	v_mad_i32_i24 v81, s13, 2, v78
	v_add_f32_e32 v36, v36, v215
	global_store_dword v81, v36, s[56:57]
	v_mad_i32_i24 v79, s13, 3, v78
	v_add_f32_e32 v37, v37, v216
	global_store_dword v79, v37, s[56:57]
	v_mad_i32_i24 v80, s13, 8, v78
	v_add_f32_e32 v38, v38, v217
	global_store_dword v80, v38, s[56:57]
	v_mad_i32_i24 v81, s13, 9, v78
	v_add_f32_e32 v39, v39, v218
	global_store_dword v81, v39, s[56:57]
	v_mad_i32_i24 v79, s13, 10, v78
	v_add_f32_e32 v40, v40, v219
	global_store_dword v79, v40, s[56:57]
	v_mad_i32_i24 v80, s13, 11, v78
	v_add_f32_e32 v41, v41, v220
	global_store_dword v80, v41, s[56:57]
	v_mad_i32_i24 v81, s13, 16, v78
	v_add_f32_e32 v42, v42, v221
	global_store_dword v81, v42, s[56:57]
	v_mad_i32_i24 v79, s13, 17, v78
	v_add_f32_e32 v43, v43, v222
	global_store_dword v79, v43, s[56:57]
	v_mad_i32_i24 v80, s13, 18, v78
	v_add_f32_e32 v44, v44, v223
	global_store_dword v80, v44, s[56:57]
	v_mad_i32_i24 v81, s13, 19, v78
	v_add_f32_e32 v45, v45, v224
	global_store_dword v81, v45, s[56:57]
	v_mad_i32_i24 v79, s13, 24, v78
	v_add_f32_e32 v46, v46, v225
	global_store_dword v79, v46, s[56:57]
	v_mad_i32_i24 v80, s13, 25, v78
	v_add_f32_e32 v47, v47, v226
	global_store_dword v80, v47, s[56:57]
	v_mad_i32_i24 v81, s13, 26, v78
	v_add_f32_e32 v48, v48, v227
	global_store_dword v81, v48, s[56:57]
	v_mad_i32_i24 v79, s13, 27, v78
	v_add_f32_e32 v49, v49, v228
	global_store_dword v79, v49, s[56:57]
	s_branch .Lys3_join
